# non-DUAL rwkv scan: y-store address kept per tile (chunk offset added once per chunk), 14 fewer instructions per chunk
# baseline (speedup 1.0000x reference)
; __device__ __forceinline__ bf16_t f2bf(float f) { return (bf16_t)(pack2(f, 0.f) & 0xffffu); }
; template <bool DUAL>
; __device__ __forceinline__ void rwkv_tile(const Params& p, int l, int tile, unsigned char* smem) {
;     ...
;         if (fr == (i & 15)) ykeep = y;
;         if ((i & 15) == 15) {
;           const int ii = (i & 16) + fr;
;           const int ri = (d == 0) ? ii + 1 : 32 - ii;
;           const int pi = plo - 1 + ri;
;           p.yR[((size_t)d * TOK + rowbase + pi) * 256 + h * 64 + row] = f2bf(ykeep);
;           if (DUAL) p.GID[((size_t)(d * 4 + b) * NSEG1 + (cix - CSPLIT) * 32 + ii) * 256 + h * 64 + row] = f2bf(gkeep);
.LBB0_1467:
	s_or_b64 exec, exec, s[50:51]
	v_and_b32_e32 v98, 15, v61
	v_bfe_u32 v66, v61, 4, 2
	v_ashrrev_i32_e32 v61, 4, v61
	v_lshl_add_u32 v62, v62, 1, 0
	v_and_b32_e32 v67, -4, v61
	v_readlane_b32 s0, v253, 62
	v_lshl_add_u32 v102, v64, 1, v62
	v_lshl_add_u32 v103, v65, 1, v62
	v_add_u32_e32 v64, 1, v61
	v_sub_u32_e32 v65, 32, v61
	v_add_u32_e32 v67, s0, v67
	v_lshlrev_b32_e32 v60, 1, v60
	s_movk_i32 s0, 0x180
	v_cndmask_b32_e64 v64, v65, v64, s[36:37]
	v_add_u32_e32 v68, 0, v60
	v_mul_lo_u32 v64, v64, s0
	s_movk_i32 s1, 0x600
	v_add_u32_e32 v104, v68, v64
	v_add3_u32 v108, 0, v64, v60
	v_mul_lo_u32 v64, v61, s1
	v_add_u32_e32 v65, 17, v61
	v_sub_u32_e32 v61, 16, v61
	v_cndmask_b32_e64 v61, v61, v65, s[36:37]
	v_or_b32_e32 v88, v67, v66
	v_lshl_add_u32 v101, v63, 1, v62
	v_mul_lo_u32 v63, v96, s0
	v_mul_lo_u32 v61, v61, s0
	v_readlane_b32 s0, v254, 35
	v_ashrrev_i32_e32 v89, 31, v88
	v_readlane_b32 s1, v254, 36
	v_add_u32_e32 v69, v68, v60
	v_add3_u32 v113, 0, v61, v60
	v_lshl_add_u64 v[90:91], v[88:89], 1, s[0:1]
	v_add_u32_e32 v60, v67, v66
	v_readlane_b32 s0, v255, 26
	v_lshlrev_b32_e32 v70, 4, v98
	v_add_u32_e32 v109, v68, v61
	v_lshl_add_u32 v89, v60, 2, s0
	v_readlane_b32 s0, v255, 27
	v_mov_b32_e32 v165, v164
	v_lshlrev_b32_e32 v97, 2, v98
	v_add_u32_e32 v99, 0, v70
	v_lshl_add_u32 v100, v88, 2, 0
	v_add_u32_e32 v105, 0xfffffe80, v104
	v_add_u32_e32 v106, 0xffffff00, v104
	v_add_u32_e32 v107, 0xffffff80, v104
	v_add_u32_e32 v110, 0xfffffe80, v109
	v_add_u32_e32 v111, 0xffffff00, v109
	v_add_u32_e32 v112, 0xffffff80, v109
	v_add_u32_e32 v114, s0, v70
	v_add_u32_e32 v115, v69, v64
	v_add_u32_e32 v116, v62, v63
	v_mov_b64_e32 v[60:61], v[164:165]
	v_mov_b64_e32 v[62:63], v[164:165]
	v_readlane_b32 s28, v254, 17
	s_waitcnt vmcnt(0) lgkmcnt(0)
	s_barrier
	v_lshlrev_b32_e32 v242, 10, v93
	v_mov_b32_e32 v243, v164
	v_lshlrev_b32_e32 v244, 10, v94
	v_mov_b32_e32 v245, v164
	v_lshlrev_b32_e32 v246, 10, v95
	v_mov_b32_e32 v247, v164
	v_lshlrev_b32_e32 v248, 10, v96
	v_mov_b32_e32 v249, v164
	v_add_u32_e32 v238, 1, v98
	v_sub_u32_e32 v240, 32, v98
	v_cndmask_b32_e64 v238, v240, v238, s[36:37]
	v_add_u32_e32 v240, 17, v98
	v_sub_u32_e32 v239, 16, v98
	v_cndmask_b32_e64 v240, v239, v240, s[36:37]
	v_sub_u32_e32 v240, v240, v238
	v_ashrrev_i32_e32 v241, 31, v240
	v_lshlrev_b64 v[240:241], 9, v[240:241]
	v_ashrrev_i32_e32 v239, 31, v238
	v_lshl_add_u64 v[238:239], s[20:21], 0, v[238:239]
	v_lshlrev_b64 v[238:239], 9, v[238:239]
	v_lshl_add_u64 v[238:239], v[90:91], 0, v[238:239]

; template <bool DUAL>
; __device__ __forceinline__ void rwkv_tile(const Params& p, int l, int tile, unsigned char* smem) {
;     ...
;       for (int i = 0; i < 32; ++i) {
;         const int inx = (i + 1) & 31;
;         const float4 nw4 = *(const float4*)(rp + inx * 384), nkk4 = *(const float4*)(rp + inx * 384 + 64), nkb4 = *(const float4*)(rp + inx * 384 + 128);
;         const float4 nkd4 = *(const float4*)(rp + inx * 384 + 192), nr4 = *(const float4*)(rp + inx * 384 + 256);
;         const float nv = vp[inx * 384];
;         v2f t = sA * (v2f){kk4.x, kk4.y};
;         t = sB * (v2f){kk4.z, kk4.w} + t;
;         float sa = t.x + t.y, ia = 0.f;
;         if (DUAL) {
;           v2f ti = iA * (v2f){kk4.x, kk4.y};
;           ti = iB * (v2f){kk4.z, kk4.w} + ti;
;           ia = ti.x + ti.y;
;           sa += dppf<0xB1>(sa); ia += dppf<0xB1>(ia);
;           sa += dppf<0x4E>(sa); ia += dppf<0x4E>(ia);
;           sa += dppf<0x141>(sa); ia += dppf<0x141>(ia);
;           sa += dppf<0x140>(sa); ia += dppf<0x140>(ia);
;         } else {
;           sa = sum16(sa);
;         }
;         v2f cA = sA * (v2f){w4.x, w4.y} + (v2f){kd4.x, kd4.y} * v;
;         v2f cB = sB * (v2f){w4.z, w4.w} + (v2f){kd4.z, kd4.w} * v;
;         sA = cA - (v2f){kb4.x, kb4.y} * sa;
;         sB = cB - (v2f){kb4.z, kb4.w} * sa;
;         v2f u = sA * (v2f){r4.x, r4.y};
;         u = sB * (v2f){r4.z, r4.w} + u;
;         float y = u.x + u.y, g = 0.f;
;         if (DUAL) {
;           iA = iA * (v2f){w4.x, w4.y} - (v2f){kb4.x, kb4.y} * ia;
;           iB = iB * (v2f){w4.z, w4.w} - (v2f){kb4.z, kb4.w} * ia;
;           v2f ui = iA * (v2f){r4.x, r4.y};
;           ui = iB * (v2f){r4.z, r4.w} + ui;
;           g = ui.x + ui.y;
;           y += dppf<0xB1>(y); g += dppf<0xB1>(g);
;           y += dppf<0x4E>(y); g += dppf<0x4E>(g);
;           y += dppf<0x141>(y); g += dppf<0x141>(g);
;           y += dppf<0x140>(y); g += dppf<0x140>(g);
.Lrw_nd_scan:
	s_ashr_i32 s101, s28, 31
	s_mov_b32 s100, s28
	s_lshl_b64 s[100:101], s[100:101], 9
	v_lshl_add_u64 v[74:75], v[238:239], 0, s[100:101]
	v_mov_b32_e32 v72, v99
	v_mov_b32_e32 v73, v100
	v_add_u32_e32 v68, 0x6000, v99
	v_add_u32_e32 v69, 0x6000, v100
	v_mov_b32_e32 v71, v98
	s_mov_b32 vcc_lo, 0xcccccccc
	s_mov_b32 vcc_hi, 0xcccccccc
	s_mov_b32 s58, 0xaaaaaaaa
	s_mov_b32 s59, 0xaaaaaaaa
	ds_read_b128 v[220:223], v72 offset:25600
	ds_read_b128 v[216:219], v72 offset:25344
	ds_read_b128 v[228:231], v72 offset:26112
	ds_read_b32 v236, v73 offset:26624
	ds_read_b128 v[224:227], v72 offset:25856
	ds_read_b128 v[232:235], v72 offset:26368
	ds_read_b128 v[122:125], v72 offset:27136
	ds_read_b128 v[118:121], v72 offset:26880
	ds_read_b128 v[130:133], v72 offset:27648
	ds_read_b32 v138, v73 offset:28160
	ds_read_b128 v[126:129], v72 offset:27392
	ds_read_b128 v[134:137], v72 offset:27904
	s_mov_b32 s50, 0
.Lrw_nd_loop:
	s_waitcnt lgkmcnt(6)
	v_pk_mul_f32 v[64:65], v[60:61], v[220:221]
	v_pk_fma_f32 v[64:65], v[62:63], v[222:223], v[64:65]
	v_add_f32_e32 v64, v64, v65
	v_pk_mul_f32 v[60:61], v[60:61], v[216:217]
	v_pk_mul_f32 v[62:63], v[62:63], v[218:219]
	v_add_f32_dpp v64, v64, v64 quad_perm:[1,0,3,2] row_mask:0xf bank_mask:0xf bound_ctrl:1
	v_pk_fma_f32 v[60:61], v[236:237], v[228:229], v[60:61] op_sel_hi:[0,1,1]
	v_pk_fma_f32 v[62:63], v[236:237], v[230:231], v[62:63] op_sel_hi:[0,1,1]
	v_add_f32_dpp v64, v64, v64 quad_perm:[2,3,0,1] row_mask:0xf bank_mask:0xf bound_ctrl:1
	ds_read_b128 v[220:223], v72 offset:28672
	ds_read_b128 v[216:219], v72 offset:28416
	v_add_f32_dpp v64, v64, v64 row_half_mirror row_mask:0xf bank_mask:0xf bound_ctrl:1
	ds_read_b128 v[228:231], v72 offset:29184
	ds_read_b32 v236, v73 offset:29696
	v_add_f32_dpp v64, v64, v64 row_mirror row_mask:0xf bank_mask:0xf bound_ctrl:1
	v_pk_fma_f32 v[60:61], v[224:225], v[64:65], v[60:61] op_sel_hi:[1,0,1] neg_lo:[1,0,0] neg_hi:[1,0,0]
	v_pk_fma_f32 v[62:63], v[226:227], v[64:65], v[62:63] op_sel_hi:[1,0,1] neg_lo:[1,0,0] neg_hi:[1,0,0]
	ds_read_b128 v[224:227], v72 offset:28928
	v_pk_mul_f32 v[66:67], v[232:233], v[60:61]
	v_pk_fma_f32 v[66:67], v[234:235], v[62:63], v[66:67]
	ds_read_b128 v[232:235], v72 offset:29440
	v_add_f32_e32 v140, v66, v67
	s_waitcnt lgkmcnt(6)
	v_pk_mul_f32 v[64:65], v[60:61], v[122:123]
	v_pk_fma_f32 v[64:65], v[62:63], v[124:125], v[64:65]
	v_add_f32_e32 v64, v64, v65
	v_pk_mul_f32 v[60:61], v[60:61], v[118:119]
	v_pk_mul_f32 v[62:63], v[62:63], v[120:121]
	v_add_f32_dpp v64, v64, v64 quad_perm:[1,0,3,2] row_mask:0xf bank_mask:0xf bound_ctrl:1
	v_pk_fma_f32 v[60:61], v[138:139], v[130:131], v[60:61] op_sel_hi:[0,1,1]
	v_pk_fma_f32 v[62:63], v[138:139], v[132:133], v[62:63] op_sel_hi:[0,1,1]
	v_add_f32_dpp v64, v64, v64 quad_perm:[2,3,0,1] row_mask:0xf bank_mask:0xf bound_ctrl:1
	ds_read_b128 v[122:125], v72 offset:30208
	ds_read_b128 v[118:121], v72 offset:29952
	v_add_f32_dpp v64, v64, v64 row_half_mirror row_mask:0xf bank_mask:0xf bound_ctrl:1
	ds_read_b128 v[130:133], v72 offset:30720
	ds_read_b32 v138, v73 offset:31232
	v_add_f32_dpp v64, v64, v64 row_mirror row_mask:0xf bank_mask:0xf bound_ctrl:1
	v_pk_fma_f32 v[60:61], v[126:127], v[64:65], v[60:61] op_sel_hi:[1,0,1] neg_lo:[1,0,0] neg_hi:[1,0,0]
	v_pk_fma_f32 v[62:63], v[128:129], v[64:65], v[62:63] op_sel_hi:[1,0,1] neg_lo:[1,0,0] neg_hi:[1,0,0]
	ds_read_b128 v[126:129], v72 offset:30464
	v_pk_mul_f32 v[66:67], v[134:135], v[60:61]
	v_pk_fma_f32 v[66:67], v[136:137], v[62:63], v[66:67]
	ds_read_b128 v[134:137], v72 offset:30976
	v_add_f32_e32 v141, v66, v67
	s_waitcnt lgkmcnt(6)
	v_pk_mul_f32 v[64:65], v[60:61], v[220:221]
	v_pk_fma_f32 v[64:65], v[62:63], v[222:223], v[64:65]
	v_add_f32_e32 v64, v64, v65
	v_pk_mul_f32 v[60:61], v[60:61], v[216:217]
	v_pk_mul_f32 v[62:63], v[62:63], v[218:219]
	v_add_f32_dpp v64, v64, v64 quad_perm:[1,0,3,2] row_mask:0xf bank_mask:0xf bound_ctrl:1
	v_pk_fma_f32 v[60:61], v[236:237], v[228:229], v[60:61] op_sel_hi:[0,1,1]
	v_pk_fma_f32 v[62:63], v[236:237], v[230:231], v[62:63] op_sel_hi:[0,1,1]
	v_add_f32_dpp v64, v64, v64 quad_perm:[2,3,0,1] row_mask:0xf bank_mask:0xf bound_ctrl:1
	ds_read_b128 v[220:223], v72 offset:31744
	ds_read_b128 v[216:219], v72 offset:31488
	v_add_f32_dpp v64, v64, v64 row_half_mirror row_mask:0xf bank_mask:0xf bound_ctrl:1
	ds_read_b128 v[228:231], v72 offset:32256
	ds_read_b32 v236, v73 offset:32768
	v_add_f32_dpp v64, v64, v64 row_mirror row_mask:0xf bank_mask:0xf bound_ctrl:1
	v_pk_fma_f32 v[60:61], v[224:225], v[64:65], v[60:61] op_sel_hi:[1,0,1] neg_lo:[1,0,0] neg_hi:[1,0,0]
	v_pk_fma_f32 v[62:63], v[226:227], v[64:65], v[62:63] op_sel_hi:[1,0,1] neg_lo:[1,0,0] neg_hi:[1,0,0]
	ds_read_b128 v[224:227], v72 offset:32000
	v_pk_mul_f32 v[66:67], v[232:233], v[60:61]
	v_pk_fma_f32 v[66:67], v[234:235], v[62:63], v[66:67]
	ds_read_b128 v[232:235], v72 offset:32512
	v_add_f32_e32 v142, v66, v67
	s_waitcnt lgkmcnt(6)
	v_pk_mul_f32 v[64:65], v[60:61], v[122:123]
	v_pk_fma_f32 v[64:65], v[62:63], v[124:125], v[64:65]
	v_add_f32_e32 v64, v64, v65
	v_pk_mul_f32 v[60:61], v[60:61], v[118:119]
	v_pk_mul_f32 v[62:63], v[62:63], v[120:121]
	v_add_f32_dpp v64, v64, v64 quad_perm:[1,0,3,2] row_mask:0xf bank_mask:0xf bound_ctrl:1
	v_pk_fma_f32 v[60:61], v[138:139], v[130:131], v[60:61] op_sel_hi:[0,1,1]
	v_pk_fma_f32 v[62:63], v[138:139], v[132:133], v[62:63] op_sel_hi:[0,1,1]
	v_add_f32_dpp v64, v64, v64 quad_perm:[2,3,0,1] row_mask:0xf bank_mask:0xf bound_ctrl:1
	ds_read_b128 v[122:125], v72 offset:33280
	ds_read_b128 v[118:121], v72 offset:33024
	v_add_f32_dpp v64, v64, v64 row_half_mirror row_mask:0xf bank_mask:0xf bound_ctrl:1
	ds_read_b128 v[130:133], v72 offset:33792
	ds_read_b32 v138, v73 offset:34304
	v_add_f32_dpp v64, v64, v64 row_mirror row_mask:0xf bank_mask:0xf bound_ctrl:1
	v_pk_fma_f32 v[60:61], v[126:127], v[64:65], v[60:61] op_sel_hi:[1,0,1] neg_lo:[1,0,0] neg_hi:[1,0,0]
	v_pk_fma_f32 v[62:63], v[128:129], v[64:65], v[62:63] op_sel_hi:[1,0,1] neg_lo:[1,0,0] neg_hi:[1,0,0]
	ds_read_b128 v[126:129], v72 offset:33536
	v_pk_mul_f32 v[66:67], v[134:135], v[60:61]
	v_pk_fma_f32 v[66:67], v[136:137], v[62:63], v[66:67]
	ds_read_b128 v[134:137], v72 offset:34048
	v_add_f32_e32 v143, v66, v67
	s_waitcnt lgkmcnt(6)
; template <bool DUAL>
; __device__ __forceinline__ void rwkv_tile(const Params& p, int l, int tile, unsigned char* smem) {
;     ...
;       for (int i = 0; i < 32; ++i) {
;         const int inx = (i + 1) & 31;
;         const float4 nw4 = *(const float4*)(rp + inx * 384), nkk4 = *(const float4*)(rp + inx * 384 + 64), nkb4 = *(const float4*)(rp + inx * 384 + 128);
;         const float4 nkd4 = *(const float4*)(rp + inx * 384 + 192), nr4 = *(const float4*)(rp + inx * 384 + 256);
;         const float nv = vp[inx * 384];
;         v2f t = sA * (v2f){kk4.x, kk4.y};
;         t = sB * (v2f){kk4.z, kk4.w} + t;
;         float sa = t.x + t.y, ia = 0.f;
;         if (DUAL) {
;           v2f ti = iA * (v2f){kk4.x, kk4.y};
;           ti = iB * (v2f){kk4.z, kk4.w} + ti;
;           ia = ti.x + ti.y;
;           sa += dppf<0xB1>(sa); ia += dppf<0xB1>(ia);
;           sa += dppf<0x4E>(sa); ia += dppf<0x4E>(ia);
;           sa += dppf<0x141>(sa); ia += dppf<0x141>(ia);
;           sa += dppf<0x140>(sa); ia += dppf<0x140>(ia);
;         } else {
;           sa = sum16(sa);
;         }
;         v2f cA = sA * (v2f){w4.x, w4.y} + (v2f){kd4.x, kd4.y} * v;
;         v2f cB = sB * (v2f){w4.z, w4.w} + (v2f){kd4.z, kd4.w} * v;
;         sA = cA - (v2f){kb4.x, kb4.y} * sa;
;         sB = cB - (v2f){kb4.z, kb4.w} * sa;
;         v2f u = sA * (v2f){r4.x, r4.y};
;         u = sB * (v2f){r4.z, r4.w} + u;
;         float y = u.x + u.y, g = 0.f;
;         if (DUAL) {
;           iA = iA * (v2f){w4.x, w4.y} - (v2f){kb4.x, kb4.y} * ia;
;           iB = iB * (v2f){w4.z, w4.w} - (v2f){kb4.z, kb4.w} * ia;
;           v2f ui = iA * (v2f){r4.x, r4.y};
;           ui = iB * (v2f){r4.z, r4.w} + ui;
;           g = ui.x + ui.y;
;           y += dppf<0xB1>(y); g += dppf<0xB1>(g);
;           y += dppf<0x4E>(y); g += dppf<0x4E>(g);
;           y += dppf<0x141>(y); g += dppf<0x141>(g);
;           y += dppf<0x140>(y); g += dppf<0x140>(g);
	v_pk_mul_f32 v[64:65], v[60:61], v[220:221]
	v_pk_fma_f32 v[64:65], v[62:63], v[222:223], v[64:65]
	v_add_f32_e32 v64, v64, v65
	v_pk_mul_f32 v[60:61], v[60:61], v[216:217]
	v_pk_mul_f32 v[62:63], v[62:63], v[218:219]
	v_add_f32_dpp v64, v64, v64 quad_perm:[1,0,3,2] row_mask:0xf bank_mask:0xf bound_ctrl:1
	v_pk_fma_f32 v[60:61], v[236:237], v[228:229], v[60:61] op_sel_hi:[0,1,1]
	v_pk_fma_f32 v[62:63], v[236:237], v[230:231], v[62:63] op_sel_hi:[0,1,1]
	v_add_f32_dpp v64, v64, v64 quad_perm:[2,3,0,1] row_mask:0xf bank_mask:0xf bound_ctrl:1
	ds_read_b128 v[220:223], v72 offset:34816
	ds_read_b128 v[216:219], v72 offset:34560
	v_add_f32_dpp v64, v64, v64 row_half_mirror row_mask:0xf bank_mask:0xf bound_ctrl:1
	ds_read_b128 v[228:231], v72 offset:35328
	ds_read_b32 v236, v73 offset:35840
	v_add_f32_dpp v64, v64, v64 row_mirror row_mask:0xf bank_mask:0xf bound_ctrl:1
	v_pk_fma_f32 v[60:61], v[224:225], v[64:65], v[60:61] op_sel_hi:[1,0,1] neg_lo:[1,0,0] neg_hi:[1,0,0]
	v_pk_fma_f32 v[62:63], v[226:227], v[64:65], v[62:63] op_sel_hi:[1,0,1] neg_lo:[1,0,0] neg_hi:[1,0,0]
	ds_read_b128 v[224:227], v72 offset:35072
	v_pk_mul_f32 v[66:67], v[232:233], v[60:61]
	v_pk_fma_f32 v[66:67], v[234:235], v[62:63], v[66:67]
	ds_read_b128 v[232:235], v72 offset:35584
	v_add_f32_e32 v144, v66, v67
	s_waitcnt lgkmcnt(6)
	v_pk_mul_f32 v[64:65], v[60:61], v[122:123]
	v_pk_fma_f32 v[64:65], v[62:63], v[124:125], v[64:65]
	v_add_f32_e32 v64, v64, v65
	v_pk_mul_f32 v[60:61], v[60:61], v[118:119]
	v_pk_mul_f32 v[62:63], v[62:63], v[120:121]
	v_add_f32_dpp v64, v64, v64 quad_perm:[1,0,3,2] row_mask:0xf bank_mask:0xf bound_ctrl:1
	v_pk_fma_f32 v[60:61], v[138:139], v[130:131], v[60:61] op_sel_hi:[0,1,1]
	v_pk_fma_f32 v[62:63], v[138:139], v[132:133], v[62:63] op_sel_hi:[0,1,1]
	v_add_f32_dpp v64, v64, v64 quad_perm:[2,3,0,1] row_mask:0xf bank_mask:0xf bound_ctrl:1
	ds_read_b128 v[122:125], v72 offset:36352
	ds_read_b128 v[118:121], v72 offset:36096
	v_add_f32_dpp v64, v64, v64 row_half_mirror row_mask:0xf bank_mask:0xf bound_ctrl:1
	ds_read_b128 v[130:133], v72 offset:36864
	ds_read_b32 v138, v73 offset:37376
	v_add_f32_dpp v64, v64, v64 row_mirror row_mask:0xf bank_mask:0xf bound_ctrl:1
	v_pk_fma_f32 v[60:61], v[126:127], v[64:65], v[60:61] op_sel_hi:[1,0,1] neg_lo:[1,0,0] neg_hi:[1,0,0]
	v_pk_fma_f32 v[62:63], v[128:129], v[64:65], v[62:63] op_sel_hi:[1,0,1] neg_lo:[1,0,0] neg_hi:[1,0,0]
	ds_read_b128 v[126:129], v72 offset:36608
	v_pk_mul_f32 v[66:67], v[134:135], v[60:61]
	v_pk_fma_f32 v[66:67], v[136:137], v[62:63], v[66:67]
	ds_read_b128 v[134:137], v72 offset:37120
	v_add_f32_e32 v145, v66, v67
	s_waitcnt lgkmcnt(6)
	v_pk_mul_f32 v[64:65], v[60:61], v[220:221]
	v_pk_fma_f32 v[64:65], v[62:63], v[222:223], v[64:65]
	v_add_f32_e32 v64, v64, v65
	v_pk_mul_f32 v[60:61], v[60:61], v[216:217]
	v_pk_mul_f32 v[62:63], v[62:63], v[218:219]
	v_add_f32_dpp v64, v64, v64 quad_perm:[1,0,3,2] row_mask:0xf bank_mask:0xf bound_ctrl:1
	v_pk_fma_f32 v[60:61], v[236:237], v[228:229], v[60:61] op_sel_hi:[0,1,1]
	v_pk_fma_f32 v[62:63], v[236:237], v[230:231], v[62:63] op_sel_hi:[0,1,1]
	v_add_f32_dpp v64, v64, v64 quad_perm:[2,3,0,1] row_mask:0xf bank_mask:0xf bound_ctrl:1
	ds_read_b128 v[220:223], v72 offset:37888
	ds_read_b128 v[216:219], v72 offset:37632
	v_add_f32_dpp v64, v64, v64 row_half_mirror row_mask:0xf bank_mask:0xf bound_ctrl:1
	ds_read_b128 v[228:231], v72 offset:38400
	ds_read_b32 v236, v73 offset:38912
	v_add_f32_dpp v64, v64, v64 row_mirror row_mask:0xf bank_mask:0xf bound_ctrl:1
	v_pk_fma_f32 v[60:61], v[224:225], v[64:65], v[60:61] op_sel_hi:[1,0,1] neg_lo:[1,0,0] neg_hi:[1,0,0]
	v_pk_fma_f32 v[62:63], v[226:227], v[64:65], v[62:63] op_sel_hi:[1,0,1] neg_lo:[1,0,0] neg_hi:[1,0,0]
	ds_read_b128 v[224:227], v72 offset:38144
	v_pk_mul_f32 v[66:67], v[232:233], v[60:61]
	v_pk_fma_f32 v[66:67], v[234:235], v[62:63], v[66:67]
	ds_read_b128 v[232:235], v72 offset:38656
	v_add_f32_e32 v146, v66, v67
	s_waitcnt lgkmcnt(6)
	v_pk_mul_f32 v[64:65], v[60:61], v[122:123]
	v_pk_fma_f32 v[64:65], v[62:63], v[124:125], v[64:65]
	v_add_f32_e32 v64, v64, v65
	v_pk_mul_f32 v[60:61], v[60:61], v[118:119]
	v_pk_mul_f32 v[62:63], v[62:63], v[120:121]
	v_add_f32_dpp v64, v64, v64 quad_perm:[1,0,3,2] row_mask:0xf bank_mask:0xf bound_ctrl:1
	v_pk_fma_f32 v[60:61], v[138:139], v[130:131], v[60:61] op_sel_hi:[0,1,1]
	v_pk_fma_f32 v[62:63], v[138:139], v[132:133], v[62:63] op_sel_hi:[0,1,1]
	v_add_f32_dpp v64, v64, v64 quad_perm:[2,3,0,1] row_mask:0xf bank_mask:0xf bound_ctrl:1
	ds_read_b128 v[122:125], v72 offset:39424
	ds_read_b128 v[118:121], v72 offset:39168
	v_add_f32_dpp v64, v64, v64 row_half_mirror row_mask:0xf bank_mask:0xf bound_ctrl:1
	ds_read_b128 v[130:133], v72 offset:39936
	ds_read_b32 v138, v73 offset:40448
	v_add_f32_dpp v64, v64, v64 row_mirror row_mask:0xf bank_mask:0xf bound_ctrl:1
	v_pk_fma_f32 v[60:61], v[126:127], v[64:65], v[60:61] op_sel_hi:[1,0,1] neg_lo:[1,0,0] neg_hi:[1,0,0]
	v_pk_fma_f32 v[62:63], v[128:129], v[64:65], v[62:63] op_sel_hi:[1,0,1] neg_lo:[1,0,0] neg_hi:[1,0,0]
	ds_read_b128 v[126:129], v72 offset:39680
	v_pk_mul_f32 v[66:67], v[134:135], v[60:61]
	v_pk_fma_f32 v[66:67], v[136:137], v[62:63], v[66:67]
	ds_read_b128 v[134:137], v72 offset:40192
	v_add_f32_e32 v147, v66, v67
	s_waitcnt lgkmcnt(6)
; template <bool DUAL>
; __device__ __forceinline__ void rwkv_tile(const Params& p, int l, int tile, unsigned char* smem) {
;     ...
;       for (int i = 0; i < 32; ++i) {
;         const int inx = (i + 1) & 31;
;         const float4 nw4 = *(const float4*)(rp + inx * 384), nkk4 = *(const float4*)(rp + inx * 384 + 64), nkb4 = *(const float4*)(rp + inx * 384 + 128);
;         const float4 nkd4 = *(const float4*)(rp + inx * 384 + 192), nr4 = *(const float4*)(rp + inx * 384 + 256);
;         const float nv = vp[inx * 384];
;         v2f t = sA * (v2f){kk4.x, kk4.y};
;         t = sB * (v2f){kk4.z, kk4.w} + t;
;         float sa = t.x + t.y, ia = 0.f;
;         if (DUAL) {
;           v2f ti = iA * (v2f){kk4.x, kk4.y};
;           ti = iB * (v2f){kk4.z, kk4.w} + ti;
;           ia = ti.x + ti.y;
;           sa += dppf<0xB1>(sa); ia += dppf<0xB1>(ia);
;           sa += dppf<0x4E>(sa); ia += dppf<0x4E>(ia);
;           sa += dppf<0x141>(sa); ia += dppf<0x141>(ia);
;           sa += dppf<0x140>(sa); ia += dppf<0x140>(ia);
;         } else {
;           sa = sum16(sa);
;         }
;         v2f cA = sA * (v2f){w4.x, w4.y} + (v2f){kd4.x, kd4.y} * v;
;         v2f cB = sB * (v2f){w4.z, w4.w} + (v2f){kd4.z, kd4.w} * v;
;         sA = cA - (v2f){kb4.x, kb4.y} * sa;
;         sB = cB - (v2f){kb4.z, kb4.w} * sa;
;         v2f u = sA * (v2f){r4.x, r4.y};
;         u = sB * (v2f){r4.z, r4.w} + u;
;         float y = u.x + u.y, g = 0.f;
;         if (DUAL) {
;           iA = iA * (v2f){w4.x, w4.y} - (v2f){kb4.x, kb4.y} * ia;
;           iB = iB * (v2f){w4.z, w4.w} - (v2f){kb4.z, kb4.w} * ia;
;           v2f ui = iA * (v2f){r4.x, r4.y};
;           ui = iB * (v2f){r4.z, r4.w} + ui;
;           g = ui.x + ui.y;
;           y += dppf<0xB1>(y); g += dppf<0xB1>(g);
;           y += dppf<0x4E>(y); g += dppf<0x4E>(g);
;           y += dppf<0x141>(y); g += dppf<0x141>(g);
;           y += dppf<0x140>(y); g += dppf<0x140>(g);
	v_pk_mul_f32 v[64:65], v[60:61], v[220:221]
	v_pk_fma_f32 v[64:65], v[62:63], v[222:223], v[64:65]
	v_add_f32_e32 v64, v64, v65
	v_pk_mul_f32 v[60:61], v[60:61], v[216:217]
	v_pk_mul_f32 v[62:63], v[62:63], v[218:219]
	v_add_f32_dpp v64, v64, v64 quad_perm:[1,0,3,2] row_mask:0xf bank_mask:0xf bound_ctrl:1
	v_pk_fma_f32 v[60:61], v[236:237], v[228:229], v[60:61] op_sel_hi:[0,1,1]
	v_pk_fma_f32 v[62:63], v[236:237], v[230:231], v[62:63] op_sel_hi:[0,1,1]
	v_add_f32_dpp v64, v64, v64 quad_perm:[2,3,0,1] row_mask:0xf bank_mask:0xf bound_ctrl:1
	ds_read_b128 v[220:223], v72 offset:40960
	ds_read_b128 v[216:219], v72 offset:40704
	v_add_f32_dpp v64, v64, v64 row_half_mirror row_mask:0xf bank_mask:0xf bound_ctrl:1
	ds_read_b128 v[228:231], v72 offset:41472
	ds_read_b32 v236, v73 offset:41984
	v_add_f32_dpp v64, v64, v64 row_mirror row_mask:0xf bank_mask:0xf bound_ctrl:1
	v_pk_fma_f32 v[60:61], v[224:225], v[64:65], v[60:61] op_sel_hi:[1,0,1] neg_lo:[1,0,0] neg_hi:[1,0,0]
	v_pk_fma_f32 v[62:63], v[226:227], v[64:65], v[62:63] op_sel_hi:[1,0,1] neg_lo:[1,0,0] neg_hi:[1,0,0]
	ds_read_b128 v[224:227], v72 offset:41216
	v_pk_mul_f32 v[66:67], v[232:233], v[60:61]
	v_pk_fma_f32 v[66:67], v[234:235], v[62:63], v[66:67]
	ds_read_b128 v[232:235], v72 offset:41728
	v_add_f32_e32 v148, v66, v67
	s_waitcnt lgkmcnt(6)
	v_pk_mul_f32 v[64:65], v[60:61], v[122:123]
	v_pk_fma_f32 v[64:65], v[62:63], v[124:125], v[64:65]
	v_add_f32_e32 v64, v64, v65
	v_pk_mul_f32 v[60:61], v[60:61], v[118:119]
	v_pk_mul_f32 v[62:63], v[62:63], v[120:121]
	v_add_f32_dpp v64, v64, v64 quad_perm:[1,0,3,2] row_mask:0xf bank_mask:0xf bound_ctrl:1
	v_pk_fma_f32 v[60:61], v[138:139], v[130:131], v[60:61] op_sel_hi:[0,1,1]
	v_pk_fma_f32 v[62:63], v[138:139], v[132:133], v[62:63] op_sel_hi:[0,1,1]
	v_add_f32_dpp v64, v64, v64 quad_perm:[2,3,0,1] row_mask:0xf bank_mask:0xf bound_ctrl:1
	ds_read_b128 v[122:125], v72 offset:42496
	ds_read_b128 v[118:121], v72 offset:42240
	v_add_f32_dpp v64, v64, v64 row_half_mirror row_mask:0xf bank_mask:0xf bound_ctrl:1
	ds_read_b128 v[130:133], v72 offset:43008
	ds_read_b32 v138, v73 offset:43520
	v_add_f32_dpp v64, v64, v64 row_mirror row_mask:0xf bank_mask:0xf bound_ctrl:1
	v_pk_fma_f32 v[60:61], v[126:127], v[64:65], v[60:61] op_sel_hi:[1,0,1] neg_lo:[1,0,0] neg_hi:[1,0,0]
	v_pk_fma_f32 v[62:63], v[128:129], v[64:65], v[62:63] op_sel_hi:[1,0,1] neg_lo:[1,0,0] neg_hi:[1,0,0]
	ds_read_b128 v[126:129], v72 offset:42752
	v_pk_mul_f32 v[66:67], v[134:135], v[60:61]
	v_pk_fma_f32 v[66:67], v[136:137], v[62:63], v[66:67]
	ds_read_b128 v[134:137], v72 offset:43264
	v_add_f32_e32 v149, v66, v67
	s_waitcnt lgkmcnt(6)
	v_pk_mul_f32 v[64:65], v[60:61], v[220:221]
	v_pk_fma_f32 v[64:65], v[62:63], v[222:223], v[64:65]
	v_add_f32_e32 v64, v64, v65
	v_pk_mul_f32 v[60:61], v[60:61], v[216:217]
	v_pk_mul_f32 v[62:63], v[62:63], v[218:219]
	v_add_f32_dpp v64, v64, v64 quad_perm:[1,0,3,2] row_mask:0xf bank_mask:0xf bound_ctrl:1
	v_pk_fma_f32 v[60:61], v[236:237], v[228:229], v[60:61] op_sel_hi:[0,1,1]
	v_pk_fma_f32 v[62:63], v[236:237], v[230:231], v[62:63] op_sel_hi:[0,1,1]
	v_add_f32_dpp v64, v64, v64 quad_perm:[2,3,0,1] row_mask:0xf bank_mask:0xf bound_ctrl:1
	ds_read_b128 v[220:223], v72 offset:44032
	ds_read_b128 v[216:219], v72 offset:43776
	v_add_f32_dpp v64, v64, v64 row_half_mirror row_mask:0xf bank_mask:0xf bound_ctrl:1
	ds_read_b128 v[228:231], v72 offset:44544
	ds_read_b32 v236, v73 offset:45056
	v_add_f32_dpp v64, v64, v64 row_mirror row_mask:0xf bank_mask:0xf bound_ctrl:1
	v_pk_fma_f32 v[60:61], v[224:225], v[64:65], v[60:61] op_sel_hi:[1,0,1] neg_lo:[1,0,0] neg_hi:[1,0,0]
	v_pk_fma_f32 v[62:63], v[226:227], v[64:65], v[62:63] op_sel_hi:[1,0,1] neg_lo:[1,0,0] neg_hi:[1,0,0]
	ds_read_b128 v[224:227], v72 offset:44288
	v_pk_mul_f32 v[66:67], v[232:233], v[60:61]
	v_pk_fma_f32 v[66:67], v[234:235], v[62:63], v[66:67]
	ds_read_b128 v[232:235], v72 offset:44800
	v_add_f32_e32 v150, v66, v67
	s_waitcnt lgkmcnt(6)
	v_pk_mul_f32 v[64:65], v[60:61], v[122:123]
	v_pk_fma_f32 v[64:65], v[62:63], v[124:125], v[64:65]
	v_add_f32_e32 v64, v64, v65
	v_pk_mul_f32 v[60:61], v[60:61], v[118:119]
	v_pk_mul_f32 v[62:63], v[62:63], v[120:121]
	v_add_f32_dpp v64, v64, v64 quad_perm:[1,0,3,2] row_mask:0xf bank_mask:0xf bound_ctrl:1
	v_pk_fma_f32 v[60:61], v[138:139], v[130:131], v[60:61] op_sel_hi:[0,1,1]
	v_pk_fma_f32 v[62:63], v[138:139], v[132:133], v[62:63] op_sel_hi:[0,1,1]
	v_add_f32_dpp v64, v64, v64 quad_perm:[2,3,0,1] row_mask:0xf bank_mask:0xf bound_ctrl:1
	ds_read_b128 v[122:125], v72 offset:45568
	ds_read_b128 v[118:121], v72 offset:45312
	v_add_f32_dpp v64, v64, v64 row_half_mirror row_mask:0xf bank_mask:0xf bound_ctrl:1
	ds_read_b128 v[130:133], v72 offset:46080
	ds_read_b32 v138, v73 offset:46592
	v_add_f32_dpp v64, v64, v64 row_mirror row_mask:0xf bank_mask:0xf bound_ctrl:1
	v_pk_fma_f32 v[60:61], v[126:127], v[64:65], v[60:61] op_sel_hi:[1,0,1] neg_lo:[1,0,0] neg_hi:[1,0,0]
	v_pk_fma_f32 v[62:63], v[128:129], v[64:65], v[62:63] op_sel_hi:[1,0,1] neg_lo:[1,0,0] neg_hi:[1,0,0]
	ds_read_b128 v[126:129], v72 offset:45824
	v_pk_mul_f32 v[66:67], v[134:135], v[60:61]
	v_pk_fma_f32 v[66:67], v[136:137], v[62:63], v[66:67]
	ds_read_b128 v[134:137], v72 offset:46336
	v_add_f32_e32 v151, v66, v67
	s_waitcnt lgkmcnt(6)
; template <bool DUAL>
; __device__ __forceinline__ void rwkv_tile(const Params& p, int l, int tile, unsigned char* smem) {
;     ...
;       for (int i = 0; i < 32; ++i) {
;         const int inx = (i + 1) & 31;
;         const float4 nw4 = *(const float4*)(rp + inx * 384), nkk4 = *(const float4*)(rp + inx * 384 + 64), nkb4 = *(const float4*)(rp + inx * 384 + 128);
;         const float4 nkd4 = *(const float4*)(rp + inx * 384 + 192), nr4 = *(const float4*)(rp + inx * 384 + 256);
;         const float nv = vp[inx * 384];
;         v2f t = sA * (v2f){kk4.x, kk4.y};
;         t = sB * (v2f){kk4.z, kk4.w} + t;
;         float sa = t.x + t.y, ia = 0.f;
;         if (DUAL) {
;           v2f ti = iA * (v2f){kk4.x, kk4.y};
;           ti = iB * (v2f){kk4.z, kk4.w} + ti;
;           ia = ti.x + ti.y;
;           sa += dppf<0xB1>(sa); ia += dppf<0xB1>(ia);
;           sa += dppf<0x4E>(sa); ia += dppf<0x4E>(ia);
;           sa += dppf<0x141>(sa); ia += dppf<0x141>(ia);
;           sa += dppf<0x140>(sa); ia += dppf<0x140>(ia);
;         } else {
;           sa = sum16(sa);
;         }
;         v2f cA = sA * (v2f){w4.x, w4.y} + (v2f){kd4.x, kd4.y} * v;
;         v2f cB = sB * (v2f){w4.z, w4.w} + (v2f){kd4.z, kd4.w} * v;
;         sA = cA - (v2f){kb4.x, kb4.y} * sa;
;         sB = cB - (v2f){kb4.z, kb4.w} * sa;
;         v2f u = sA * (v2f){r4.x, r4.y};
;         u = sB * (v2f){r4.z, r4.w} + u;
;         float y = u.x + u.y, g = 0.f;
;         if (DUAL) {
;           iA = iA * (v2f){w4.x, w4.y} - (v2f){kb4.x, kb4.y} * ia;
;           iB = iB * (v2f){w4.z, w4.w} - (v2f){kb4.z, kb4.w} * ia;
;           v2f ui = iA * (v2f){r4.x, r4.y};
;           ui = iB * (v2f){r4.z, r4.w} + ui;
;           g = ui.x + ui.y;
;           y += dppf<0xB1>(y); g += dppf<0xB1>(g);
;           y += dppf<0x4E>(y); g += dppf<0x4E>(g);
;           y += dppf<0x141>(y); g += dppf<0x141>(g);
;           y += dppf<0x140>(y); g += dppf<0x140>(g);
	v_pk_mul_f32 v[64:65], v[60:61], v[220:221]
	v_pk_fma_f32 v[64:65], v[62:63], v[222:223], v[64:65]
	v_add_f32_e32 v64, v64, v65
	v_pk_mul_f32 v[60:61], v[60:61], v[216:217]
	v_pk_mul_f32 v[62:63], v[62:63], v[218:219]
	v_add_f32_dpp v64, v64, v64 quad_perm:[1,0,3,2] row_mask:0xf bank_mask:0xf bound_ctrl:1
	v_pk_fma_f32 v[60:61], v[236:237], v[228:229], v[60:61] op_sel_hi:[0,1,1]
	v_pk_fma_f32 v[62:63], v[236:237], v[230:231], v[62:63] op_sel_hi:[0,1,1]
	v_add_f32_dpp v64, v64, v64 quad_perm:[2,3,0,1] row_mask:0xf bank_mask:0xf bound_ctrl:1
	ds_read_b128 v[220:223], v72 offset:47104
	ds_read_b128 v[216:219], v72 offset:46848
	v_add_f32_dpp v64, v64, v64 row_half_mirror row_mask:0xf bank_mask:0xf bound_ctrl:1
	ds_read_b128 v[228:231], v72 offset:47616
	ds_read_b32 v236, v73 offset:48128
	v_add_f32_dpp v64, v64, v64 row_mirror row_mask:0xf bank_mask:0xf bound_ctrl:1
	v_pk_fma_f32 v[60:61], v[224:225], v[64:65], v[60:61] op_sel_hi:[1,0,1] neg_lo:[1,0,0] neg_hi:[1,0,0]
	v_pk_fma_f32 v[62:63], v[226:227], v[64:65], v[62:63] op_sel_hi:[1,0,1] neg_lo:[1,0,0] neg_hi:[1,0,0]
	ds_read_b128 v[224:227], v72 offset:47360
	v_pk_mul_f32 v[66:67], v[232:233], v[60:61]
	v_pk_fma_f32 v[66:67], v[234:235], v[62:63], v[66:67]
	ds_read_b128 v[232:235], v72 offset:47872
	v_add_f32_e32 v152, v66, v67
	s_waitcnt lgkmcnt(6)
	v_pk_mul_f32 v[64:65], v[60:61], v[122:123]
	v_pk_fma_f32 v[64:65], v[62:63], v[124:125], v[64:65]
	v_add_f32_e32 v64, v64, v65
	v_pk_mul_f32 v[60:61], v[60:61], v[118:119]
	v_pk_mul_f32 v[62:63], v[62:63], v[120:121]
	v_add_f32_dpp v64, v64, v64 quad_perm:[1,0,3,2] row_mask:0xf bank_mask:0xf bound_ctrl:1
	v_pk_fma_f32 v[60:61], v[138:139], v[130:131], v[60:61] op_sel_hi:[0,1,1]
	v_pk_fma_f32 v[62:63], v[138:139], v[132:133], v[62:63] op_sel_hi:[0,1,1]
	v_add_f32_dpp v64, v64, v64 quad_perm:[2,3,0,1] row_mask:0xf bank_mask:0xf bound_ctrl:1
	ds_read_b128 v[122:125], v72 offset:48640
	ds_read_b128 v[118:121], v72 offset:48384
	v_add_f32_dpp v64, v64, v64 row_half_mirror row_mask:0xf bank_mask:0xf bound_ctrl:1
	ds_read_b128 v[130:133], v72 offset:49152
	ds_read_b32 v138, v73 offset:49664
	v_add_f32_dpp v64, v64, v64 row_mirror row_mask:0xf bank_mask:0xf bound_ctrl:1
	v_pk_fma_f32 v[60:61], v[126:127], v[64:65], v[60:61] op_sel_hi:[1,0,1] neg_lo:[1,0,0] neg_hi:[1,0,0]
	v_pk_fma_f32 v[62:63], v[128:129], v[64:65], v[62:63] op_sel_hi:[1,0,1] neg_lo:[1,0,0] neg_hi:[1,0,0]
	ds_read_b128 v[126:129], v72 offset:48896
	v_pk_mul_f32 v[66:67], v[134:135], v[60:61]
	v_pk_fma_f32 v[66:67], v[136:137], v[62:63], v[66:67]
	ds_read_b128 v[134:137], v72 offset:49408
	v_add_f32_e32 v153, v66, v67
	s_waitcnt lgkmcnt(6)
	v_pk_mul_f32 v[64:65], v[60:61], v[220:221]
	v_pk_fma_f32 v[64:65], v[62:63], v[222:223], v[64:65]
	v_add_f32_e32 v64, v64, v65
	v_pk_mul_f32 v[60:61], v[60:61], v[216:217]
	v_pk_mul_f32 v[62:63], v[62:63], v[218:219]
	v_add_f32_dpp v64, v64, v64 quad_perm:[1,0,3,2] row_mask:0xf bank_mask:0xf bound_ctrl:1
	v_pk_fma_f32 v[60:61], v[236:237], v[228:229], v[60:61] op_sel_hi:[0,1,1]
	v_pk_fma_f32 v[62:63], v[236:237], v[230:231], v[62:63] op_sel_hi:[0,1,1]
	v_add_f32_dpp v64, v64, v64 quad_perm:[2,3,0,1] row_mask:0xf bank_mask:0xf bound_ctrl:1
	ds_read_b128 v[220:223], v68 offset:25600
	ds_read_b128 v[216:219], v68 offset:25344
	v_add_f32_dpp v64, v64, v64 row_half_mirror row_mask:0xf bank_mask:0xf bound_ctrl:1
	ds_read_b128 v[228:231], v68 offset:26112
	ds_read_b32 v236, v69 offset:26624
	v_add_f32_dpp v64, v64, v64 row_mirror row_mask:0xf bank_mask:0xf bound_ctrl:1
	v_pk_fma_f32 v[60:61], v[224:225], v[64:65], v[60:61] op_sel_hi:[1,0,1] neg_lo:[1,0,0] neg_hi:[1,0,0]
	v_pk_fma_f32 v[62:63], v[226:227], v[64:65], v[62:63] op_sel_hi:[1,0,1] neg_lo:[1,0,0] neg_hi:[1,0,0]
	ds_read_b128 v[224:227], v68 offset:25856
	v_pk_mul_f32 v[66:67], v[232:233], v[60:61]
	v_pk_fma_f32 v[66:67], v[234:235], v[62:63], v[66:67]
	ds_read_b128 v[232:235], v68 offset:26368
	v_add_f32_e32 v154, v66, v67
	s_waitcnt lgkmcnt(6)
; __device__ __forceinline__ bf16_t f2bf(float f) { return (bf16_t)(pack2(f, 0.f) & 0xffffu); }
; template <bool DUAL>
; __device__ __forceinline__ void rwkv_tile(const Params& p, int l, int tile, unsigned char* smem) {
;     ...
;         v2f u = sA * (v2f){r4.x, r4.y};
;         u = sB * (v2f){r4.z, r4.w} + u;
;         float y = u.x + u.y, g = 0.f;
;         if (DUAL) {
;           iA = iA * (v2f){w4.x, w4.y} - (v2f){kb4.x, kb4.y} * ia;
;           iB = iB * (v2f){w4.z, w4.w} - (v2f){kb4.z, kb4.w} * ia;
;           v2f ui = iA * (v2f){r4.x, r4.y};
;           ui = iB * (v2f){r4.z, r4.w} + ui;
;           g = ui.x + ui.y;
;           y += dppf<0xB1>(y); g += dppf<0xB1>(g);
;           y += dppf<0x4E>(y); g += dppf<0x4E>(g);
;           y += dppf<0x141>(y); g += dppf<0x141>(g);
;           y += dppf<0x140>(y); g += dppf<0x140>(g);
;           if (fr == (i & 15)) gkeep = g;
;         } else {
;           y = sum16(y);
;         }
;         if (fr == (i & 15)) ykeep = y;
;         if ((i & 15) == 15) {
;           const int ii = (i & 16) + fr;
;           const int ri = (d == 0) ? ii + 1 : 32 - ii;
;           const int pi = plo - 1 + ri;
;           p.yR[((size_t)d * TOK + rowbase + pi) * 256 + h * 64 + row] = f2bf(ykeep);
;           if (DUAL) p.GID[((size_t)(d * 4 + b) * NSEG1 + (cix - CSPLIT) * 32 + ii) * 256 + h * 64 + row] = f2bf(gkeep);
;         }
;         w4 = nw4; kk4 = nkk4; kb4 = nkb4; kd4 = nkd4; r4 = nr4; v = nv;
	v_pk_mul_f32 v[64:65], v[60:61], v[122:123]
	v_pk_fma_f32 v[64:65], v[62:63], v[124:125], v[64:65]
	v_add_f32_e32 v64, v64, v65
	v_pk_mul_f32 v[60:61], v[60:61], v[118:119]
	v_pk_mul_f32 v[62:63], v[62:63], v[120:121]
	v_add_f32_dpp v64, v64, v64 quad_perm:[1,0,3,2] row_mask:0xf bank_mask:0xf bound_ctrl:1
	v_pk_fma_f32 v[60:61], v[138:139], v[130:131], v[60:61] op_sel_hi:[0,1,1]
	v_pk_fma_f32 v[62:63], v[138:139], v[132:133], v[62:63] op_sel_hi:[0,1,1]
	v_add_f32_dpp v64, v64, v64 quad_perm:[2,3,0,1] row_mask:0xf bank_mask:0xf bound_ctrl:1
	ds_read_b128 v[122:125], v68 offset:27136
	ds_read_b128 v[118:121], v68 offset:26880
	v_add_f32_dpp v64, v64, v64 row_half_mirror row_mask:0xf bank_mask:0xf bound_ctrl:1
	ds_read_b128 v[130:133], v68 offset:27648
	ds_read_b32 v138, v69 offset:28160
	v_add_f32_dpp v64, v64, v64 row_mirror row_mask:0xf bank_mask:0xf bound_ctrl:1
	v_pk_fma_f32 v[60:61], v[126:127], v[64:65], v[60:61] op_sel_hi:[1,0,1] neg_lo:[1,0,0] neg_hi:[1,0,0]
	v_pk_fma_f32 v[62:63], v[128:129], v[64:65], v[62:63] op_sel_hi:[1,0,1] neg_lo:[1,0,0] neg_hi:[1,0,0]
	ds_read_b128 v[126:129], v68 offset:27392
	v_pk_mul_f32 v[66:67], v[134:135], v[60:61]
	v_pk_fma_f32 v[66:67], v[136:137], v[62:63], v[66:67]
	ds_read_b128 v[134:137], v68 offset:27904
	v_add_f32_e32 v155, v66, v67
	v_add_f32_dpp v140, v140, v140 row_shl:8 row_mask:0xf bank_mask:0x3
	v_add_f32_dpp v140, v148, v148 row_shr:8 row_mask:0xf bank_mask:0xc
	v_add_f32_dpp v141, v141, v141 row_shl:8 row_mask:0xf bank_mask:0x3
	v_add_f32_dpp v141, v149, v149 row_shr:8 row_mask:0xf bank_mask:0xc
	v_add_f32_dpp v142, v142, v142 row_shl:8 row_mask:0xf bank_mask:0x3
	v_add_f32_dpp v142, v150, v150 row_shr:8 row_mask:0xf bank_mask:0xc
	v_add_f32_dpp v143, v143, v143 row_shl:8 row_mask:0xf bank_mask:0x3
	v_add_f32_dpp v143, v151, v151 row_shr:8 row_mask:0xf bank_mask:0xc
	v_add_f32_dpp v144, v144, v144 row_shl:8 row_mask:0xf bank_mask:0x3
	v_add_f32_dpp v144, v152, v152 row_shr:8 row_mask:0xf bank_mask:0xc
	v_add_f32_dpp v145, v145, v145 row_shl:8 row_mask:0xf bank_mask:0x3
	v_add_f32_dpp v145, v153, v153 row_shr:8 row_mask:0xf bank_mask:0xc
	v_add_f32_dpp v146, v146, v146 row_shl:8 row_mask:0xf bank_mask:0x3
	v_add_f32_dpp v146, v154, v154 row_shr:8 row_mask:0xf bank_mask:0xc
	v_add_f32_dpp v147, v147, v147 row_shl:8 row_mask:0xf bank_mask:0x3
	v_add_f32_dpp v147, v155, v155 row_shr:8 row_mask:0xf bank_mask:0xc
	v_add_f32_dpp v140, v140, v140 row_shl:4 row_mask:0xf bank_mask:0x5
	v_add_f32_dpp v140, v144, v144 row_shr:4 row_mask:0xf bank_mask:0xa
	v_add_f32_dpp v141, v141, v141 row_shl:4 row_mask:0xf bank_mask:0x5
	v_add_f32_dpp v141, v145, v145 row_shr:4 row_mask:0xf bank_mask:0xa
	v_add_f32_dpp v142, v142, v142 row_shl:4 row_mask:0xf bank_mask:0x5
	v_add_f32_dpp v142, v146, v146 row_shr:4 row_mask:0xf bank_mask:0xa
	v_add_f32_dpp v143, v143, v143 row_shl:4 row_mask:0xf bank_mask:0x5
	v_add_f32_dpp v143, v147, v147 row_shr:4 row_mask:0xf bank_mask:0xa
	v_cndmask_b32_e32 v156, v140, v142, vcc
	v_cndmask_b32_e32 v157, v142, v140, vcc
	v_cndmask_b32_e32 v159, v143, v141, vcc
	v_cndmask_b32_e32 v158, v141, v143, vcc
	v_add_f32_dpp v156, v157, v156 quad_perm:[2,3,0,1] row_mask:0xf bank_mask:0xf
	v_add_f32_dpp v158, v159, v158 quad_perm:[2,3,0,1] row_mask:0xf bank_mask:0xf
	v_cndmask_b32_e64 v160, v156, v158, s[58:59]
	v_cndmask_b32_e64 v161, v158, v156, s[58:59]
	v_add_u32_e32 v72, 0x6000, v72
	v_add_u32_e32 v73, 0x6000, v73
	v_add_f32_dpp v70, v161, v160 quad_perm:[1,0,3,2] row_mask:0xf bank_mask:0xf
	v_mov_b32_e32 v68, v99
	v_mov_b32_e32 v69, v100
	v_cvt_pk_bf16_f32 v76, v70, v70
	global_store_short v[74:75], v76, off
	s_nop 1
	v_lshl_add_u64 v[74:75], v[74:75], 0, v[240:241]
	s_add_i32 s50, s50, 1
	s_cmp_lg_u32 s50, 2
	s_cbranch_scc1 .Lrw_nd_loop
	s_branch .LBB0_1491
